# P1 sample-row GEMM loop: the next call's 24 operand loads are issued once the staging registers are free, hiding their latency under the reduction and epilogue
# baseline (speedup 1.0000x reference)
; __host__ __device__ __forceinline__ int permcol(int c) { return perm12(c >> 8) * 256 + (c & 255); }
; __global__ void __launch_bounds__(512, 2) hymba_fwd(Params p) {
;     ...
;         for (int u = bx; u < 16 * 48; u += G) { const int rb = u / 48, ct = u % 48; int br0, br1;
;             if (ct < 32) { br0 = ct * 64; br1 = br0 + 32; } else { br0 = 2048 + ((ct - 32) >> 2) * 256 + ((ct - 32) & 3) * 32; br1 = br0 + 128; }
;             small_gemm<DM>(lds, g.A, g.Bt, MP + 32 * rb, permcol(br0), permcol(br1), E); }
.LBB0_234:
	s_mov_b32 s101, 0
	s_mov_b32 s6, 0x76981032
	s_lshl_b32 s0, s2, 6
	s_lshl_b32 s1, s66, 6
	s_lshl_b32 s3, s2, 5
	s_lshl_b32 s18, s66, 5
	s_mov_b32 s7, 0xba54
	s_movk_i32 s19, 0x100
	v_mov_b32_e32 v41, 0
	s_movk_i32 s20, 0x90
	s_movk_i32 s21, 0x7ff
	s_movk_i32 s22, 0x7f
	s_mov_b32 s23, s2
	s_barrier
	s_branch .LBB0_237

; #define HG_MFMA(a, b, c) __builtin_amdgcn_mfma_f32_32x32x16_bf16((a), (b), (c), 0, 0, 0)
; __host__ __device__ __forceinline__ int permcol(int c) { return perm12(c >> 8) * 256 + (c & 255); }
;     __device__ __forceinline__ void small_pre(int row, int c0, int c1, SPre& sp) const { sp.ss = sumsq2[row]; sp.h0 = unpack4(*(const u32x2*)(HB + (size_t)row * DM + c0)); sp.h1 = unpack4(*(const u32x2*)(HB + (size_t)row * DM + c1)); }
; template <int K, class Epi>
; __device__ __forceinline__ void small_gemm(unsigned char* lds, const bf16_t* A, const bf16_t* Bt, int row0, int br0, int br1, const Epi& E) {
;     ...
;     const bf16_t* ap = A + (size_t)(row0 + r) * K + k0; const bf16_t* b0p = Bt + (size_t)(br0 + r) * K + k0; const bf16_t* b1p = Bt + (size_t)(br1 + r) * K + k0;
;     typename Epi::SPre spre; const int srow = row0 + ((tid >> 3) & 31), sc4 = (tid & 7) * 4;
;     if (tid < 256) E.small_pre(srow, br0 + sc4, br1 + sc4, spre);
;     f32x16 acc0, acc1;
; #pragma unroll
;     for (int i = 0; i < 16; ++i) { acc0[i] = 0.f; acc1[i] = 0.f; }
; #pragma unroll UNR
;     for (int s = 0; s < NS; ++s) { const bf16x8 a = *(const bf16x8*)(ap + 16 * s), b0 = *(const bf16x8*)(b0p + 16 * s), b1 = *(const bf16x8*)(b1p + 16 * s);
;         acc0 = HG_MFMA(a, b0, acc0); acc1 = HG_MFMA(a, b1, acc1); }
; __global__ void __launch_bounds__(512, 2) hymba_fwd(Params p) {
;     ...
;         for (int u = bx; u < 16 * 48; u += G) { const int rb = u / 48, ct = u % 48; int br0, br1;
;             if (ct < 32) { br0 = ct * 64; br1 = br0 + 32; } else { br0 = 2048 + ((ct - 32) >> 2) * 256 + ((ct - 32) & 3) * 32; br1 = br0 + 128; }
;             small_gemm<DM>(lds, g.A, g.Bt, MP + 32 * rb, permcol(br0), permcol(br1), E); }
.LBB0_245:
	s_or_b64 exec, exec, s[12:13]
	s_lshl_b32 s14, s16, 5
	s_add_i32 s4, s14, 0x4000
	v_and_b32_e32 v76, 31, v44
	v_bfe_u32 v77, v44, 5, 1
	s_ashr_i32 s5, s25, 6
	s_waitcnt lgkmcnt(0)
	s_lshl_b32 s37, s5, 8
	s_lshl_b32 s36, s4, 11
	s_add_i32 s36, s36, s37
	s_add_u32 s38, s82, s36
	s_addc_u32 s39, s83, 0
	s_lshl_b32 s36, s17, 11
	s_add_i32 s36, s36, s37
	s_add_u32 s40, s64, s36
	s_addc_u32 s41, s65, 0
	s_lshl_b32 s36, s24, 11
	s_add_i32 s36, s36, s37
	s_add_u32 s42, s64, s36
	s_addc_u32 s43, s65, 0
	v_and_b32_e32 v60, 63, v44
	v_lshrrev_b32_e32 v61, 4, v60
	v_and_b32_e32 v62, 7, v60
	v_xor_b32_e32 v62, v62, v61
	v_lshrrev_b32_e32 v61, 3, v60
	v_lshlrev_b32_e32 v62, 4, v62
	v_lshl_or_b32 v64, v61, 11, v62
	v_xor_b32_e32 v65, 64, v64
	v_add_u32_e32 v65, 0x4000, v65
	v_add_u32_e32 v66, 0x8000, v64
	v_xor_b32_e32 v67, 64, v64
	v_add_u32_e32 v67, 0xc000, v67
	s_cmp_eq_u32 s101, 1
	s_cbranch_scc1 .Lsgp_have
	global_load_dwordx4 v[88:91], v64, s[38:39]
	global_load_dwordx4 v[92:95], v65, s[38:39]
	global_load_dwordx4 v[96:99], v66, s[38:39]
	global_load_dwordx4 v[100:103], v67, s[38:39]
	global_load_dwordx4 v[104:107], v64, s[40:41]
	global_load_dwordx4 v[108:111], v65, s[40:41]
	global_load_dwordx4 v[112:115], v66, s[40:41]
	global_load_dwordx4 v[116:119], v67, s[40:41]
	global_load_dwordx4 v[120:123], v64, s[42:43]
	global_load_dwordx4 v[124:127], v65, s[42:43]
	global_load_dwordx4 v[128:131], v66, s[42:43]
	global_load_dwordx4 v[132:135], v67, s[42:43]
	global_load_dwordx4 v[136:139], v64, s[38:39] offset:128
	global_load_dwordx4 v[140:143], v65, s[38:39] offset:128
	global_load_dwordx4 v[144:147], v66, s[38:39] offset:128
	global_load_dwordx4 v[148:151], v67, s[38:39] offset:128
	global_load_dwordx4 v[152:155], v64, s[40:41] offset:128
	global_load_dwordx4 v[156:159], v65, s[40:41] offset:128
	global_load_dwordx4 v[160:163], v66, s[40:41] offset:128
	global_load_dwordx4 v[164:167], v67, s[40:41] offset:128
	global_load_dwordx4 v[168:171], v64, s[42:43] offset:128
	global_load_dwordx4 v[172:175], v65, s[42:43] offset:128
	global_load_dwordx4 v[180:183], v66, s[42:43] offset:128
	global_load_dwordx4 v[184:187], v67, s[42:43] offset:128
.Lsgp_have:
	s_mov_b32 s101, 0
	s_mul_i32 s46, s5, 0x3000
	v_lshl_add_u32 v68, v60, 4, s46
	v_lshl_add_u32 v69, v76, 7, s46
	v_bfe_u32 v63, v76, 1, 3
	v_or_b32_e32 v46, 0, v77
	v_xor_b32_e32 v46, v46, v63
	v_lshl_add_u32 v46, v46, 4, v69
	v_or_b32_e32 v47, 2, v77
	v_xor_b32_e32 v47, v47, v63
	v_lshl_add_u32 v47, v47, 4, v69
	v_or_b32_e32 v48, 4, v77
	v_xor_b32_e32 v48, v48, v63
	v_lshl_add_u32 v48, v48, 4, v69
	v_or_b32_e32 v49, 6, v77
	v_xor_b32_e32 v49, v49, v63
	v_lshl_add_u32 v49, v49, 4, v69
	s_mulk_i32 s5, 0x2400
	v_lshlrev_b32_e32 v40, 2, v76
	s_add_i32 s5, s5, 0
	v_mul_u32_u24_e32 v58, 0x90, v77
	v_lshlrev_b32_e32 v54, 2, v58
	v_add3_u32 v55, s5, v40, v54
	v_add3_u32 v40, s5, v54, v40
	v_add_u32_e32 v54, 0x1000, v40
	v_add_u32_e32 v56, 0x400, v55
	v_add_u32_e32 v57, 0x1400, v40
	v_add_u32_e32 v58, 0xc00, v55
	v_add_u32_e32 v59, 0x1e00, v40
	s_waitcnt vmcnt(12)
	ds_write_b128 v68, v[88:91]
	ds_write_b128 v68, v[92:95] offset:1024
	ds_write_b128 v68, v[96:99] offset:2048
	ds_write_b128 v68, v[100:103] offset:3072
	ds_write_b128 v68, v[104:107] offset:4096
	ds_write_b128 v68, v[108:111] offset:5120
	ds_write_b128 v68, v[112:115] offset:6144
	ds_write_b128 v68, v[116:119] offset:7168
	ds_write_b128 v68, v[120:123] offset:8192
	ds_write_b128 v68, v[124:127] offset:9216
	ds_write_b128 v68, v[128:131] offset:10240
	ds_write_b128 v68, v[132:135] offset:11264
	s_waitcnt lgkmcnt(0)
	ds_read_b128 v[192:195], v46
	ds_read_b128 v[212:215], v46 offset:4096
	ds_read_b128 v[228:231], v46 offset:8192
	ds_read_b128 v[196:199], v47
	ds_read_b128 v[216:219], v47 offset:4096
	ds_read_b128 v[232:235], v47 offset:8192
	ds_read_b128 v[200:203], v48
	ds_read_b128 v[220:223], v48 offset:4096
	ds_read_b128 v[236:239], v48 offset:8192
	ds_read_b128 v[208:211], v49
	ds_read_b128 v[224:227], v49 offset:4096
	ds_read_b128 v[240:243], v49 offset:8192
	s_waitcnt lgkmcnt(9)
	v_mfma_f32_32x32x16_bf16 v[0:15], v[192:195], v[212:215], 0
	v_mfma_f32_32x32x16_bf16 v[16:31], v[192:195], v[228:231], 0
	s_waitcnt lgkmcnt(6)
	v_mfma_f32_32x32x16_bf16 v[0:15], v[196:199], v[216:219], v[0:15]
	v_mfma_f32_32x32x16_bf16 v[16:31], v[196:199], v[232:235], v[16:31]
	s_waitcnt lgkmcnt(3)
	v_mfma_f32_32x32x16_bf16 v[0:15], v[200:203], v[220:223], v[0:15]
	v_mfma_f32_32x32x16_bf16 v[16:31], v[200:203], v[236:239], v[16:31]
	s_waitcnt lgkmcnt(0)
	v_mfma_f32_32x32x16_bf16 v[0:15], v[208:211], v[224:227], v[0:15]
	v_mfma_f32_32x32x16_bf16 v[16:31], v[208:211], v[240:243], v[16:31]
	s_waitcnt vmcnt(0)
	ds_write_b128 v68, v[136:139]
	ds_write_b128 v68, v[140:143] offset:1024
	ds_write_b128 v68, v[144:147] offset:2048
	ds_write_b128 v68, v[148:151] offset:3072
	ds_write_b128 v68, v[152:155] offset:4096
	ds_write_b128 v68, v[156:159] offset:5120
	ds_write_b128 v68, v[160:163] offset:6144
	ds_write_b128 v68, v[164:167] offset:7168
	ds_write_b128 v68, v[168:171] offset:8192
	ds_write_b128 v68, v[172:175] offset:9216
	ds_write_b128 v68, v[180:183] offset:10240
	ds_write_b128 v68, v[184:187] offset:11264
	s_waitcnt lgkmcnt(0)
	s_add_i32 s36, s23, s66
	s_cmpk_gt_i32 s36, 0x2ff
	s_cbranch_scc1 .Lsgp_none
	s_mul_hi_i32 s46, s36, 0x2aaaaaab
	s_lshr_b32 s99, s46, 31
	s_ashr_i32 s46, s46, 3
	s_add_i32 s46, s46, s99
	s_mul_i32 s99, s46, 48
	s_sub_i32 s36, s36, s99
	s_lshl_b32 s46, s46, 5
	s_addk_i32 s46, 0x4000
	s_lshl_b32 s46, s46, 11
	s_add_i32 s46, s46, s37
	s_add_u32 s38, s82, s46
	s_addc_u32 s39, s83, 0
	s_cmp_lt_i32 s36, 32
	s_cbranch_scc0 .Lsgp_glu
	s_lshl_b32 s46, s36, 6
	s_add_i32 s99, s46, 32
	s_branch .Lsgp_cols
; __host__ __device__ __forceinline__ int perm12(int s) { return (int)((0xBA5476981032ull >> (4 * s)) & 15ull); }
; __host__ __device__ __forceinline__ int permcol(int c) { return perm12(c >> 8) * 256 + (c & 255); }
; __global__ void __launch_bounds__(512, 2) hymba_fwd(Params p) {
;     ...
;         for (int u = bx; u < 16 * 48; u += G) { const int rb = u / 48, ct = u % 48; int br0, br1;
;             if (ct < 32) { br0 = ct * 64; br1 = br0 + 32; } else { br0 = 2048 + ((ct - 32) >> 2) * 256 + ((ct - 32) & 3) * 32; br1 = br0 + 128; }
;             small_gemm<DM>(lds, g.A, g.Bt, MP + 32 * rb, permcol(br0), permcol(br1), E); }
.Lsgp_glu:
	s_sub_i32 s36, s36, 32
	s_lshr_b32 s46, s36, 2
	s_lshl_b32 s46, s46, 8
	s_and_b32 s99, s36, 3
	s_lshl_b32 s99, s99, 5
	s_add_i32 s46, s46, s99
	s_addk_i32 s46, 0x800
	s_add_i32 s99, s46, 0x80
.Lsgp_cols:
	s_lshr_b32 s36, s46, 8
	s_lshl_b32 s36, s36, 2
	s_lshr_b64 s[40:41], s[6:7], s36
	s_and_b32 s40, s40, 15
	s_lshl_b32 s40, s40, 8
	s_and_b32 s46, s46, 0xff
	s_or_b32 s46, s40, s46
	s_lshr_b32 s36, s99, 8
	s_lshl_b32 s36, s36, 2
	s_lshr_b64 s[42:43], s[6:7], s36
	s_and_b32 s42, s42, 15
	s_lshl_b32 s42, s42, 8
	s_and_b32 s99, s99, 0xff
	s_or_b32 s99, s42, s99
	s_lshl_b32 s46, s46, 11
	s_add_i32 s46, s46, s37
	s_add_u32 s40, s64, s46
	s_addc_u32 s41, s65, 0
	s_lshl_b32 s99, s99, 11
	s_add_i32 s99, s99, s37
	s_add_u32 s42, s64, s99
	s_addc_u32 s43, s65, 0
	global_load_dwordx4 v[88:91], v64, s[38:39]
	global_load_dwordx4 v[92:95], v65, s[38:39]
	global_load_dwordx4 v[96:99], v66, s[38:39]
	global_load_dwordx4 v[100:103], v67, s[38:39]
	global_load_dwordx4 v[104:107], v64, s[40:41]
	global_load_dwordx4 v[108:111], v65, s[40:41]
	global_load_dwordx4 v[112:115], v66, s[40:41]
	global_load_dwordx4 v[116:119], v67, s[40:41]
	global_load_dwordx4 v[120:123], v64, s[42:43]
	global_load_dwordx4 v[124:127], v65, s[42:43]
	global_load_dwordx4 v[128:131], v66, s[42:43]
	global_load_dwordx4 v[132:135], v67, s[42:43]
	global_load_dwordx4 v[136:139], v64, s[38:39] offset:128
	global_load_dwordx4 v[140:143], v65, s[38:39] offset:128
	global_load_dwordx4 v[144:147], v66, s[38:39] offset:128
	global_load_dwordx4 v[148:151], v67, s[38:39] offset:128
	global_load_dwordx4 v[152:155], v64, s[40:41] offset:128
	global_load_dwordx4 v[156:159], v65, s[40:41] offset:128
	global_load_dwordx4 v[160:163], v66, s[40:41] offset:128
	global_load_dwordx4 v[164:167], v67, s[40:41] offset:128
	global_load_dwordx4 v[168:171], v64, s[42:43] offset:128
	global_load_dwordx4 v[172:175], v65, s[42:43] offset:128
	global_load_dwordx4 v[180:183], v66, s[42:43] offset:128
	global_load_dwordx4 v[184:187], v67, s[42:43] offset:128
	s_mov_b32 s101, 1
; __device__ __forceinline__ unsigned cvt_pk_bf16(float lo, float hi) { unsigned r; asm volatile("v_cvt_pk_bf16_f32 %0, %1, %2" : "=v"(r) : "v"(lo), "v"(hi)); return r; }
; __device__ __forceinline__ float sigmoidf_(float x) { return frcp(1.0f + __expf(-x)); }
; #define HG_MFMA(a, b, c) __builtin_amdgcn_mfma_f32_32x32x16_bf16((a), (b), (c), 0, 0, 0)
; #define LDS_BARRIER() do { asm volatile("s_waitcnt lgkmcnt(0)" ::: "memory"); __builtin_amdgcn_s_barrier(); asm volatile("" ::: "memory"); } while (0)
; template <int K, class Epi>
; __device__ __forceinline__ void small_gemm(unsigned char* lds, const bf16_t* A, const bf16_t* Bt, int row0, int br0, int br1, const Epi& E) {
;     ...
;     for (int s = 0; s < NS; ++s) { const bf16x8 a = *(const bf16x8*)(ap + 16 * s), b0 = *(const bf16x8*)(b0p + 16 * s), b1 = *(const bf16x8*)(b1p + 16 * s);
;         acc0 = HG_MFMA(a, b0, acc0); acc1 = HG_MFMA(a, b1, acc1); }
;     float* part = (float*)lds + (size_t)w * (2 * 32 * SG_P);
; #pragma unroll
;     for (int g = 0; g < 4; ++g)
; #pragma unroll
;         for (int i = 0; i < 4; ++i) { part[(8 * g + 4 * hh + i) * SG_P + r] = acc0[4 * g + i]; part[(32 + 8 * g + 4 * hh + i) * SG_P + r] = acc1[4 * g + i]; }
;     LDS_BARRIER();
;     if (tid < 256) { const int row = tid >> 3, c4 = (tid & 7) * 4; f32x4 v0 = {0.f, 0.f, 0.f, 0.f}, v1 = {0.f, 0.f, 0.f, 0.f};
; #pragma unroll
;         for (int ww = 0; ww < 8; ++ww) { const float* pp = (const float*)lds + (size_t)ww * (2 * 32 * SG_P); v0 += *(const f32x4*)(pp + row * SG_P + c4); v1 += *(const f32x4*)(pp + (32 + row) * SG_P + c4); }
;         E.small(row0 + row, br0 + c4, br1 + c4, v0, v1, spre); }
;     __device__ __forceinline__ void small(int row, int c0p, int c1p, const f32x4& v0, const f32x4& v1, const SPre& sp) const {
;     ...
;         } else { const int n1 = c0 - 2048, cu = (n1 >> 8) * 128 + (n1 & 127); f32x4 uu;
; #pragma unroll
;             for (int j = 0; j < 4; ++j) uu[j] = v0[j] * sigmoidf_(v1[j]);
;             u32x2 w; w.x = cvt_pk_bf16(uu[0], uu[1]); w.y = cvt_pk_bf16(uu[2], uu[3]); *(u32x2*)(U + (size_t)row * 512 + cu) = w;
;             const int rs = row - MP; __builtin_nontemporal_store(uu, (f32x4*)(scs + ((size_t)((rs >> 2) * (CW - 1) + (CW - 1 - DS) + (rs & 3))) * MIXB + cu)); }
.Lsgp_none:
	ds_read_b128 v[192:195], v46
	ds_read_b128 v[212:215], v46 offset:4096
	ds_read_b128 v[228:231], v46 offset:8192
	ds_read_b128 v[196:199], v47
	ds_read_b128 v[216:219], v47 offset:4096
	ds_read_b128 v[232:235], v47 offset:8192
	ds_read_b128 v[200:203], v48
	ds_read_b128 v[220:223], v48 offset:4096
	ds_read_b128 v[236:239], v48 offset:8192
	ds_read_b128 v[208:211], v49
	ds_read_b128 v[224:227], v49 offset:4096
	ds_read_b128 v[240:243], v49 offset:8192
	s_waitcnt lgkmcnt(9)
	v_mfma_f32_32x32x16_bf16 v[0:15], v[192:195], v[212:215], v[0:15]
	v_mfma_f32_32x32x16_bf16 v[16:31], v[192:195], v[228:231], v[16:31]
	s_waitcnt lgkmcnt(6)
	v_mfma_f32_32x32x16_bf16 v[0:15], v[196:199], v[216:219], v[0:15]
	v_mfma_f32_32x32x16_bf16 v[16:31], v[196:199], v[232:235], v[16:31]
	s_waitcnt lgkmcnt(3)
	v_mfma_f32_32x32x16_bf16 v[0:15], v[200:203], v[220:223], v[0:15]
	v_mfma_f32_32x32x16_bf16 v[16:31], v[200:203], v[236:239], v[16:31]
	s_waitcnt lgkmcnt(0)
	v_mfma_f32_32x32x16_bf16 v[0:15], v[208:211], v[224:227], v[0:15]
	v_add_u32_e32 v50, 0x1600, v40
	v_add_u32_e32 v51, 0x800, v55
	v_add_u32_e32 v52, 0x1800, v40
	v_add_u32_e32 v53, 0x1c00, v40
	v_add_u32_e32 v40, 0x2000, v40
	v_mfma_f32_32x32x16_bf16 v[16:31], v[208:211], v[240:243], v[16:31]
	s_barrier
	s_nop 5
	ds_write2_b32 v55, v0, v1 offset1:36
	s_nop 4
	ds_write2_b32 v54, v16, v17 offset0:128 offset1:164
	ds_write2_b32 v55, v2, v3 offset0:72 offset1:108
	ds_write2_b32 v54, v18, v19 offset0:200 offset1:236
	ds_write2_b32 v56, v4, v5 offset0:32 offset1:68
	ds_write2_b32 v57, v20, v21 offset0:160 offset1:196
	ds_write2_b32 v56, v6, v7 offset0:104 offset1:140
	ds_write2_b32 v50, v22, v23 offset0:104 offset1:140
	ds_write2_b32 v51, v8, v9 offset0:64 offset1:100
	ds_write2_b32 v52, v24, v25 offset0:192 offset1:228
	ds_write2_b32 v51, v10, v11 offset0:136 offset1:172
	ds_write2_b32 v53, v26, v27 offset0:8 offset1:44
	ds_write2_b32 v58, v12, v13 offset0:96 offset1:132
	ds_write2_b32 v59, v28, v29 offset0:96 offset1:132
	ds_write2_b32 v58, v14, v15 offset0:168 offset1:204
	ds_write2_b32 v40, v30, v31 offset0:40 offset1:76
	s_waitcnt lgkmcnt(0)
	s_barrier
	s_and_saveexec_b64 s[12:13], vcc
	s_cbranch_execz .LBB0_236
	v_ashrrev_i32_e32 v10, 3, v44
	v_mul_lo_u32 v0, v10, s20
	v_lshlrev_b32_e32 v1, 2, v42
	v_add3_u32 v11, 0, v0, v1
	ds_read_b128 v[0:3], v11
	ds_read_b128 v[4:7], v11 offset:4608
	ds_read_b128 v[12:15], v11 offset:9216
	ds_read_b128 v[16:19], v11 offset:64512
	s_waitcnt lgkmcnt(0)
	v_pk_add_f32 v[8:9], v[2:3], 0 op_sel_hi:[1,0]
	v_pk_add_f32 v[20:21], v[0:1], 0 op_sel_hi:[1,0]
	ds_read_b128 v[0:3], v11 offset:13824
	v_pk_add_f32 v[22:23], v[6:7], 0 op_sel_hi:[1,0]
	v_pk_add_f32 v[24:25], v[4:5], 0 op_sel_hi:[1,0]
	ds_read_b128 v[4:7], v11 offset:18432
	v_pk_add_f32 v[8:9], v[8:9], v[14:15]
	v_pk_add_f32 v[20:21], v[20:21], v[12:13]
	s_waitcnt lgkmcnt(1)
	v_pk_add_f32 v[22:23], v[22:23], v[2:3]
	ds_read_b128 v[12:15], v11 offset:23040
	v_pk_add_f32 v[24:25], v[24:25], v[0:1]
	ds_read_b128 v[0:3], v11 offset:27648
	s_waitcnt lgkmcnt(2)
	v_pk_add_f32 v[6:7], v[8:9], v[6:7]
	v_pk_add_f32 v[8:9], v[20:21], v[4:5]
	s_waitcnt lgkmcnt(1)
	v_pk_add_f32 v[20:21], v[22:23], v[14:15]
	v_pk_add_f32 v[24:25], v[24:25], v[12:13]
	s_waitcnt lgkmcnt(0)
	v_pk_add_f32 v[26:27], v[6:7], v[2:3]
	ds_read_b128 v[2:5], v11 offset:32256
	v_pk_add_f32 v[28:29], v[8:9], v[0:1]
	ds_read_b128 v[6:9], v11 offset:36864
	v_add_u32_e32 v0, 0xfc00, v11
	ds_read_b128 v[12:15], v0 offset:4608
	s_waitcnt lgkmcnt(2)
	v_pk_add_f32 v[4:5], v[20:21], v[4:5]
	ds_read_b128 v[20:23], v11 offset:41472
	v_pk_add_f32 v[24:25], v[24:25], v[2:3]
	ds_read_b128 v[0:3], v11 offset:46080
	s_waitcnt lgkmcnt(3)
	v_pk_add_f32 v[8:9], v[26:27], v[8:9]
	v_pk_add_f32 v[26:27], v[28:29], v[6:7]
	s_waitcnt lgkmcnt(1)
	v_pk_add_f32 v[28:29], v[4:5], v[22:23]
	ds_read_b128 v[4:7], v11 offset:50688
	s_waitcnt lgkmcnt(1)
	v_pk_add_f32 v[8:9], v[8:9], v[2:3]
	v_pk_add_f32 v[26:27], v[26:27], v[0:1]
	ds_read_b128 v[0:3], v11 offset:59904
	v_pk_add_f32 v[24:25], v[24:25], v[20:21]
	ds_read_b128 v[20:23], v11 offset:55296
	s_waitcnt lgkmcnt(2)
	v_pk_add_f32 v[6:7], v[28:29], v[6:7]
	v_pk_add_f32 v[4:5], v[24:25], v[4:5]
	s_waitcnt lgkmcnt(1)
	v_pk_add_f32 v[2:3], v[6:7], v[2:3]
	v_pk_add_f32 v[4:5], v[4:5], v[0:1]
	v_pk_add_f32 v[0:1], v[2:3], v[14:15]
	v_pk_add_f32 v[2:3], v[4:5], v[12:13]
	v_and_b32_e32 v5, 0x7c, v45
	v_lshrrev_b64 v[12:13], v5, s[6:7]
	v_lshlrev_b32_e32 v11, 8, v12
	s_waitcnt lgkmcnt(0)
	v_pk_add_f32 v[8:9], v[8:9], v[22:23]
	v_pk_add_f32 v[20:21], v[26:27], v[20:21]
	v_add_u32_e32 v4, s4, v10
	v_and_b32_e32 v12, 0xf00, v11
	v_pk_add_f32 v[6:7], v[8:9], v[18:19]
	v_pk_add_f32 v[8:9], v[20:21], v[16:17]
	v_cmp_lt_u32_e32 vcc, s21, v12
	v_ashrrev_i32_e32 v5, 31, v4
	s_and_saveexec_b64 s[4:5], vcc
	s_xor_b64 s[4:5], exec, s[4:5]
	s_cbranch_execz .LBB0_248
	v_mul_f32_e32 v0, 0xbfb8aa3b, v0
	v_mul_f32_e32 v2, 0xbfb8aa3b, v2
	v_mul_f32_e32 v3, 0xbfb8aa3b, v3
	v_exp_f32_e32 v0, v0
	v_mul_f32_e32 v1, 0xbfb8aa3b, v1
	v_exp_f32_e32 v2, v2
	v_exp_f32_e32 v3, v3
	v_exp_f32_e32 v1, v1
	v_add_f32_e32 v0, 1.0, v0
	v_add_f32_e32 v2, 1.0, v2
	v_add_f32_e32 v3, 1.0, v3
	v_rcp_f32_e32 v14, v0
	v_add_f32_e32 v0, 1.0, v1
	v_rcp_f32_e32 v2, v2
	v_rcp_f32_e32 v3, v3
	v_rcp_f32_e32 v15, v0
	v_add_u32_e32 v11, 0xfffff800, v12
	v_readlane_b32 s16, v247, 36
	v_pk_mul_f32 v[0:1], v[8:9], v[2:3]
	v_pk_mul_f32 v[2:3], v[6:7], v[14:15]
	v_lshrrev_b32_e32 v6, 1, v11
	v_and_or_b32 v40, v43, s22, v6
	v_lshlrev_b64 v[4:5], 10, v[4:5]
	v_readlane_b32 s17, v247, 37
	v_lshlrev_b32_e32 v8, 1, v40
	v_mov_b32_e32 v9, v41
	v_lshl_add_u64 v[4:5], s[16:17], 0, v[4:5]
	v_lshl_add_u64 v[4:5], v[4:5], 0, v[8:9]
	v_cvt_pk_bf16_f32 v6, v0, v1
	v_cvt_pk_bf16_f32 v7, v2, v3
	global_store_dwordx2 v[4:5], v[6:7], off
	v_add_u32_e32 v4, s14, v10
	v_ashrrev_i32_e32 v4, 2, v4
	v_mul_lo_u32 v4, v4, 30
	v_bfe_u32 v5, v44, 3, 2
	v_add3_u32 v4, v5, v4, 26
	v_ashrrev_i32_e32 v5, 31, v4
	v_lshlrev_b64 v[4:5], 11, v[4:5]
	v_lshl_add_u64 v[4:5], s[8:9], 0, v[4:5]
	v_lshl_add_u64 v[4:5], v[40:41], 2, v[4:5]
	global_store_dwordx4 v[4:5], v[0:3], off nt
